# depthwise-conv phase: all next-row loads of the sliding-window loop requested one sub-step to one iteration ahead (first pair a whole iteration ahead, requested by the item head for the first iteratio
# speedup vs baseline: 1.0131x; 1.0010x over previous
; __device__ __forceinline__ u32x4 pack8(const float* v) { u32x4 w; w.x = pk2(v[0], v[1]); w.y = pk2(v[2], v[3]); w.z = pk2(v[4], v[5]); w.w = pk2(v[6], v[7]); return w; }
; __device__ __forceinline__ float siluf_(float x) { return x / (1.f + __expf(-x)); }
; __global__ void __launch_bounds__(NTHR, 2) mk_fwd(Args args) {
;     ...
;                     const int tb = idx / 352, j0 = (idx - tb * 352) * 8; const int t0 = tb * 16; const int b = (t0 >= TB) ? 1 : 0, i0 = t0 - b * TB;
;                     float wg0[8], wg1[8], wg2[8], bg[8], wv0[8], wv1[8], wv2[8], bv[8];
; #pragma unroll
;                     for (int e = 0; e < 8; ++e) { wg0[e] = cw[j0 + e]; wg1[e] = cw[FF2 + j0 + e]; wg2[e] = cw[2 * FF2 + j0 + e]; bg[e] = cb[j0 + e];
;                         wv0[e] = cw[FF + j0 + e]; wv1[e] = cw[FF2 + FF + j0 + e]; wv2[e] = cw[2 * FF2 + FF + j0 + e]; bv[e] = cb[FF + j0 + e]; }
;                     const bf16_t* up = U + (size_t)t0 * FF2 + j0;
;                     u32x4 gp_ = (u32x4){0u, 0u, 0u, 0u}, vp_ = (u32x4){0u, 0u, 0u, 0u};
;                     if (i0 != 0 && i0 != LC) { gp_ = *(const u32x4*)(up - FF2); vp_ = *(const u32x4*)(up - FF2 + FF); }
;                     u32x4 gc_ = *(const u32x4*)up, vc_ = *(const u32x4*)(up + FF);
; #pragma unroll 4
;                     for (int r = 0; r < 16; ++r) {
;                         u32x4 gn_ = (u32x4){0u, 0u, 0u, 0u}, vn_ = (u32x4){0u, 0u, 0u, 0u};
;                         const int ii = i0 + r;
;                         if (ii != LC - 1 && ii != TB - 1) { gn_ = *(const u32x4*)(up + (size_t)(r + 1) * FF2); vn_ = *(const u32x4*)(up + (size_t)(r + 1) * FF2 + FF); }
;                         float gm[8], gc[8], gn[8], vm[8], vc[8], vn[8], o[8];
;                         unpack8(gp_, gm); unpack8(gc_, gc); unpack8(gn_, gn); unpack8(vp_, vm); unpack8(vc_, vc); unpack8(vn_, vn);
; #pragma unroll
;                         for (int e = 0; e < 8; ++e) {
;                             const float a = wg0[e] * gm[e] + wg1[e] * gc[e] + wg2[e] * gn[e] + bg[e];
;                             const float v = wv0[e] * vm[e] + wv1[e] * vc[e] + wv2[e] * vn[e] + bv[e];
;                             o[e] = siluf_(a) * v;
;                         }
;                         *(u32x4*)(ACT + (size_t)(t0 + r) * FF + j0) = pack8(o);
;                         gp_ = gc_; vp_ = vc_; gc_ = gn_; vc_ = vn_;
;                     }
.LBB0_89:
	s_or_b64 exec, exec, s[0:1]
	v_add_co_u32_e32 v38, vcc, s69, v84
	s_movk_i32 s0, 0x2c00
	s_nop 0
	v_addc_co_u32_e32 v39, vcc, 0, v85, vcc
	global_load_dwordx4 v[88:91], v[84:85], off
	s_nop 0
	global_load_dwordx4 v[84:87], v[38:39], off offset:1536
	v_mad_i64_i32 v[38:39], s[0:1], v92, s0, 0
	v_and_b32_e32 v37, 0xffffdff0, v93
	v_mov_b64_e32 v[94:95], s[4:5]
	s_movk_i32 s0, 0x1600
	s_mov_b32 s18, 0
	v_lshlrev_b64 v[42:43], 1, v[42:43]
	v_mad_i64_i32 v[100:101], s[0:1], v92, s0, v[94:95]
	v_sub_u32_e32 v132, 0xfc, v37
	v_lshl_add_u64 v[102:103], s[4:5], 0, v[38:39]
	v_lshl_add_u64 v[188:189], v[102:103], 0, v[42:43]
	v_add_co_u32_e32 v184, vcc, 0x89a2000, v188
	s_nop 1
	v_addc_co_u32_e32 v185, vcc, 0, v189, vcc
	global_load_dwordx4 v[176:179], v[184:185], off offset:3072
	v_add_co_u32_e32 v186, vcc, 0x89a4000, v188
	s_nop 1
	v_addc_co_u32_e32 v187, vcc, 0, v189, vcc
	global_load_dwordx4 v[180:183], v[186:187], off offset:512
	s_waitcnt vmcnt(0)
	s_branch .LBB0_91
.LBB0_90:
	s_or_b64 exec, exec, s[0:1]
	v_pk_mul_f32 v[104:105], v[32:33], v[124:125]
	s_nop 0
	v_lshlrev_b32_e32 v38, 16, v88
	v_and_b32_e32 v39, 0xffff0000, v88
	v_pk_fma_f32 v[98:99], v[4:5], v[98:99], v[104:105]
	v_pk_mul_f32 v[122:123], v[60:61], v[122:123]
	v_pk_fma_f32 v[38:39], v[48:49], v[38:39], v[98:99]
	s_nop 0
	v_lshlrev_b32_e32 v104, 16, v84
	v_pk_add_f32 v[38:39], v[12:13], v[38:39]
	v_and_b32_e32 v105, 0xffff0000, v84
	v_mul_f32_e32 v37, 0xbfb8aa3b, v38
	v_exp_f32_e32 v98, v37
	v_mul_f32_e32 v37, 0xbfb8aa3b, v39
	v_exp_f32_e32 v99, v37
	v_pk_fma_f32 v[94:95], v[16:17], v[94:95], v[122:123]
	v_pk_mul_f32 v[106:107], v[62:63], v[106:107]
	v_pk_fma_f32 v[94:95], v[64:65], v[104:105], v[94:95]
	v_pk_add_f32 v[98:99], v[98:99], 1.0 op_sel_hi:[1,0]
	v_pk_add_f32 v[94:95], v[24:25], v[94:95]
	v_pk_fma_f32 v[106:107], v[18:19], v[110:111], v[106:107]
	v_pk_mul_f32 v[96:97], v[70:71], v[96:97]
	s_add_i32 s18, s18, 4
	v_rcp_f32_e32 v37, v99
	s_nop 0
	v_mul_f32_e32 v39, v39, v37
	v_pk_fma_f32 v[96:97], v[22:23], v[118:119], v[96:97]
	v_rcp_f32_e32 v37, v98
	s_nop 0
	v_mul_f32_e32 v38, v38, v37
	v_pk_mul_f32 v[98:99], v[34:35], v[126:127]
	v_pk_mul_f32 v[38:39], v[38:39], v[94:95]
	v_lshlrev_b32_e32 v94, 16, v89
	v_and_b32_e32 v95, 0xffff0000, v89
	v_pk_fma_f32 v[98:99], v[6:7], v[112:113], v[98:99]
	v_lshlrev_b32_e32 v104, 16, v85
	v_pk_fma_f32 v[94:95], v[50:51], v[94:95], v[98:99]
	v_and_b32_e32 v105, 0xffff0000, v85
	v_pk_add_f32 v[94:95], v[14:15], v[94:95]
	v_pk_fma_f32 v[104:105], v[66:67], v[104:105], v[106:107]
	v_mul_f32_e32 v37, 0xbfb8aa3b, v94
	v_exp_f32_e32 v98, v37
	v_mul_f32_e32 v37, 0xbfb8aa3b, v95
	v_exp_f32_e32 v99, v37
	v_pk_add_f32 v[104:105], v[26:27], v[104:105]
	s_cmp_eq_u32 s18, 16
	v_pk_add_f32 v[98:99], v[98:99], 1.0 op_sel_hi:[1,0]
	s_nop 0
	s_nop 0
	v_rcp_f32_e32 v37, v99
	s_nop 0
	v_mul_f32_e32 v95, v95, v37
	v_rcp_f32_e32 v37, v98
	s_nop 0
	v_mul_f32_e32 v94, v94, v37
	v_pk_mul_f32 v[98:99], v[94:95], v[104:105]
	v_pk_mul_f32 v[104:105], v[52:53], v[130:131]
	v_lshlrev_b32_e32 v94, 16, v90
	v_and_b32_e32 v95, 0xffff0000, v90
	v_pk_fma_f32 v[104:105], v[0:1], v[116:117], v[104:105]
	v_pk_mul_f32 v[110:111], v[68:69], v[128:129]
	v_pk_fma_f32 v[94:95], v[56:57], v[94:95], v[104:105]
	v_lshlrev_b32_e32 v106, 16, v86
	v_pk_add_f32 v[94:95], v[8:9], v[94:95]
	v_and_b32_e32 v107, 0xffff0000, v86
	v_mul_f32_e32 v37, 0xbfb8aa3b, v94
	v_exp_f32_e32 v104, v37
	v_mul_f32_e32 v37, 0xbfb8aa3b, v95
	v_exp_f32_e32 v105, v37
	v_pk_fma_f32 v[110:111], v[20:21], v[114:115], v[110:111]
	v_pk_add_f32 v[104:105], v[104:105], 1.0 op_sel_hi:[1,0]
	s_nop 0
	v_pk_fma_f32 v[106:107], v[72:73], v[106:107], v[110:111]
	v_rcp_f32_e32 v37, v105
	s_nop 0
	v_mul_f32_e32 v95, v95, v37
	v_pk_add_f32 v[106:107], v[28:29], v[106:107]
	v_rcp_f32_e32 v37, v104
	s_nop 0
	v_mul_f32_e32 v94, v94, v37
	v_pk_mul_f32 v[104:105], v[94:95], v[106:107]
	v_pk_mul_f32 v[106:107], v[54:55], v[108:109]
	v_lshlrev_b32_e32 v94, 16, v91
	v_and_b32_e32 v95, 0xffff0000, v91
	v_pk_fma_f32 v[106:107], v[2:3], v[120:121], v[106:107]
	v_lshlrev_b32_e32 v108, 16, v87
	v_pk_fma_f32 v[94:95], v[58:59], v[94:95], v[106:107]
	v_and_b32_e32 v109, 0xffff0000, v87
	v_pk_add_f32 v[94:95], v[10:11], v[94:95]
	v_pk_fma_f32 v[96:97], v[74:75], v[108:109], v[96:97]
	v_mul_f32_e32 v37, 0xbfb8aa3b, v94
	v_exp_f32_e32 v106, v37
	v_mul_f32_e32 v37, 0xbfb8aa3b, v95
	v_exp_f32_e32 v107, v37
	v_pk_add_f32 v[96:97], v[30:31], v[96:97]
	v_pk_add_f32 v[106:107], v[106:107], 1.0 op_sel_hi:[1,0]
	s_nop 0
	s_nop 0
	v_rcp_f32_e32 v37, v107
	s_nop 0
	v_mul_f32_e32 v95, v95, v37
	s_mov_b64 s[0:1], 0x5800
	v_rcp_f32_e32 v37, v106
	s_nop 0
	v_mul_f32_e32 v94, v94, v37
	v_pk_mul_f32 v[106:107], v[94:95], v[96:97]
	v_cvt_pk_bf16_f32 v94, v38, v39
	v_add_co_u32_e32 v38, vcc, 0x13f24000, v92
	v_lshl_add_u64 v[100:101], v[100:101], 0, s[0:1]
	s_mov_b64 s[0:1], 0xb000
	v_cvt_pk_bf16_f32 v95, v98, v99
	v_cvt_pk_bf16_f32 v96, v104, v105
	v_cvt_pk_bf16_f32 v97, v106, v107
	v_addc_co_u32_e32 v39, vcc, 0, v93, vcc
	v_lshl_add_u64 v[102:103], v[102:103], 0, s[0:1]
	global_store_dwordx4 v[38:39], v[94:97], off offset:512
	s_cbranch_scc1 .LBB0_86
; __device__ __forceinline__ u32x4 pack8(const float* v) { u32x4 w; w.x = pk2(v[0], v[1]); w.y = pk2(v[2], v[3]); w.z = pk2(v[4], v[5]); w.w = pk2(v[6], v[7]); return w; }
; __device__ __forceinline__ void unpack8(u32x4 w, float* v) { v[0] = bflo(w.x); v[1] = bfhi(w.x); v[2] = bflo(w.y); v[3] = bfhi(w.y); v[4] = bflo(w.z); v[5] = bfhi(w.z); v[6] = bflo(w.w); v[7] = bfhi(w.w); }
; __device__ __forceinline__ float siluf_(float x) { return x / (1.f + __expf(-x)); }
; __global__ void __launch_bounds__(NTHR, 2) mk_fwd(Args args) {
;     ...
;                     for (int r = 0; r < 16; ++r) {
;                         u32x4 gn_ = (u32x4){0u, 0u, 0u, 0u}, vn_ = (u32x4){0u, 0u, 0u, 0u};
;                         const int ii = i0 + r;
;                         if (ii != LC - 1 && ii != TB - 1) { gn_ = *(const u32x4*)(up + (size_t)(r + 1) * FF2); vn_ = *(const u32x4*)(up + (size_t)(r + 1) * FF2 + FF); }
;                         float gm[8], gc[8], gn[8], vm[8], vc[8], vn[8], o[8];
;                         unpack8(gp_, gm); unpack8(gc_, gc); unpack8(gn_, gn); unpack8(vp_, vm); unpack8(vc_, vc); unpack8(vn_, vn);
; #pragma unroll
;                         for (int e = 0; e < 8; ++e) {
;                             const float a = wg0[e] * gm[e] + wg1[e] * gc[e] + wg2[e] * gn[e] + bg[e];
;                             const float v = wv0[e] * vm[e] + wv1[e] * vc[e] + wv2[e] * vn[e] + bv[e];
;                             o[e] = siluf_(a) * v;
;                         }
;                         *(u32x4*)(ACT + (size_t)(t0 + r) * FF + j0) = pack8(o);
.LBB0_91:
	v_lshl_add_u64 v[104:105], v[102:103], 0, v[42:43]
	v_add_co_u32_e32 v38, vcc, 0x89a2000, v104
	s_waitcnt vmcnt(4)
	v_lshlrev_b32_e32 v110, 16, v88
	v_addc_co_u32_e32 v39, vcc, 0, v105, vcc
	v_mov_b32_e32 v96, v176
	v_mov_b32_e32 v97, v177
	v_mov_b32_e32 v98, v178
	v_mov_b32_e32 v99, v179
	v_add_co_u32_e32 v184, vcc, 0x89ad000, v104
	s_nop 1
	v_addc_co_u32_e32 v185, vcc, 0, v105, vcc
	global_load_dwordx4 v[176:179], v[184:185], off offset:3072
	v_add_co_u32_e32 v38, vcc, 0x89a4000, v104
	v_and_b32_e32 v111, 0xffff0000, v88
	s_nop 0
	v_addc_co_u32_e32 v39, vcc, 0, v105, vcc
	v_mov_b32_e32 v92, v180
	v_mov_b32_e32 v93, v181
	v_mov_b32_e32 v94, v182
	v_mov_b32_e32 v95, v183
	v_add_co_u32_e32 v186, vcc, 0x89af000, v104
	s_nop 1
	v_addc_co_u32_e32 v187, vcc, 0, v105, vcc
	global_load_dwordx4 v[180:183], v[186:187], off offset:512
	v_add_co_u32_e32 v140, vcc, 0x89a5000, v104
	s_nop 1
	v_addc_co_u32_e32 v141, vcc, 0, v105, vcc
	global_load_dwordx4 v[148:151], v[140:141], off offset:2048
	v_add_co_u32_e32 v142, vcc, 0x89a6000, v104
	s_nop 1
	v_addc_co_u32_e32 v143, vcc, 0, v105, vcc
	global_load_dwordx4 v[152:155], v[142:143], off offset:3584
	v_add_co_u32_e32 v144, vcc, 0x89a8000, v104
	s_nop 1
	v_addc_co_u32_e32 v145, vcc, 0, v105, vcc
	global_load_dwordx4 v[156:159], v[144:145], off offset:1024
	v_add_co_u32_e32 v146, vcc, 0x89a9000, v104
	s_nop 1
	v_addc_co_u32_e32 v147, vcc, 0, v105, vcc
	global_load_dwordx4 v[160:163], v[146:147], off offset:2560
	v_add_co_u32_e32 v172, vcc, 0x89ab000, v104
	s_nop 1
	v_addc_co_u32_e32 v173, vcc, 0, v105, vcc
	global_load_dwordx4 v[164:167], v[172:173], off
	v_add_co_u32_e32 v174, vcc, 0x89ac000, v104
	s_nop 1
	v_addc_co_u32_e32 v175, vcc, 0, v105, vcc
	global_load_dwordx4 v[168:171], v[174:175], off offset:1536
	v_lshlrev_b32_e32 v108, 16, v80
	v_and_b32_e32 v109, 0xffff0000, v80
	v_pk_mul_f32 v[116:117], v[32:33], v[110:111]
	v_lshlrev_b32_e32 v114, 16, v76
	v_pk_fma_f32 v[108:109], v[4:5], v[108:109], v[116:117]
	v_and_b32_e32 v115, 0xffff0000, v76
	v_lshlrev_b32_e32 v112, 16, v84
	v_and_b32_e32 v113, 0xffff0000, v84
	v_pk_mul_f32 v[118:119], v[60:61], v[112:113]
	v_lshlrev_b32_e32 v120, 16, v90
	v_pk_fma_f32 v[114:115], v[16:17], v[114:115], v[118:119]
	v_lshlrev_b32_e32 v118, 16, v85
	v_and_b32_e32 v119, 0xffff0000, v85
	v_and_b32_e32 v121, 0xffff0000, v90
	v_pk_mul_f32 v[124:125], v[52:53], v[120:121]
	v_lshlrev_b32_e32 v122, 16, v86
	v_and_b32_e32 v123, 0xffff0000, v86
	v_pk_mul_f32 v[126:127], v[68:69], v[122:123]
	s_nop 0
	v_lshlrev_b32_e32 v38, 16, v96
	v_and_b32_e32 v39, 0xffff0000, v96
	v_pk_fma_f32 v[108:109], v[48:49], v[38:39], v[108:109]
	v_lshlrev_b32_e32 v96, 16, v77
	v_pk_add_f32 v[108:109], v[12:13], v[108:109]
	s_nop 0
	v_lshlrev_b32_e32 v106, 16, v92
	v_mul_f32_e32 v37, 0xbfb8aa3b, v108
	v_exp_f32_e32 v116, v37
	v_mul_f32_e32 v37, 0xbfb8aa3b, v109
	v_exp_f32_e32 v117, v37
	v_and_b32_e32 v107, 0xffff0000, v92
	v_and_b32_e32 v85, 0xffff0000, v93
	v_pk_fma_f32 v[114:115], v[64:65], v[106:107], v[114:115]
	v_pk_add_f32 v[116:117], v[116:117], 1.0 op_sel_hi:[1,0]
	v_pk_add_f32 v[114:115], v[24:25], v[114:115]
	v_pk_mul_f32 v[128:129], v[60:61], v[106:107]
	v_rcp_f32_e32 v37, v117
	s_nop 0
	v_mul_f32_e32 v109, v109, v37
	v_and_b32_e32 v117, 0xffff0000, v89
	v_pk_fma_f32 v[112:113], v[16:17], v[112:113], v[128:129]
	v_rcp_f32_e32 v37, v116
	s_nop 0
	v_mul_f32_e32 v108, v108, v37
	v_lshlrev_b32_e32 v116, 16, v89
	v_lshlrev_b32_e32 v80, 16, v81
	v_and_b32_e32 v81, 0xffff0000, v81
	v_lshlrev_b32_e32 v88, 16, v97
	v_and_b32_e32 v89, 0xffff0000, v97
	v_and_b32_e32 v97, 0xffff0000, v77
	v_pk_mul_f32 v[76:77], v[34:35], v[116:117]
	v_lshlrev_b32_e32 v84, 16, v93
	v_pk_fma_f32 v[76:77], v[6:7], v[80:81], v[76:77]
	v_pk_mul_f32 v[80:81], v[62:63], v[118:119]
	v_pk_fma_f32 v[76:77], v[50:51], v[88:89], v[76:77]
	v_pk_fma_f32 v[80:81], v[18:19], v[96:97], v[80:81]
	v_pk_add_f32 v[76:77], v[14:15], v[76:77]
	v_pk_mul_f32 v[114:115], v[108:109], v[114:115]
	v_mul_f32_e32 v37, 0xbfb8aa3b, v76
	v_exp_f32_e32 v92, v37
	v_mul_f32_e32 v37, 0xbfb8aa3b, v77
	v_exp_f32_e32 v93, v37
	v_pk_fma_f32 v[80:81], v[66:67], v[84:85], v[80:81]
	v_pk_add_f32 v[92:93], v[92:93], 1.0 op_sel_hi:[1,0]
	s_nop 0
	v_pk_add_f32 v[80:81], v[26:27], v[80:81]
	v_rcp_f32_e32 v37, v93
	s_nop 0
	v_mul_f32_e32 v77, v77, v37
	v_and_b32_e32 v109, 0xffff0000, v94
	v_rcp_f32_e32 v37, v92
	s_nop 0
	v_mul_f32_e32 v76, v76, v37
	v_pk_mul_f32 v[76:77], v[76:77], v[80:81]
	v_lshlrev_b32_e32 v80, 16, v82
	v_and_b32_e32 v81, 0xffff0000, v82
	v_lshlrev_b32_e32 v96, 16, v98
	v_and_b32_e32 v97, 0xffff0000, v98
	v_pk_fma_f32 v[80:81], v[0:1], v[80:81], v[124:125]
	v_lshlrev_b32_e32 v92, 16, v78
	v_pk_fma_f32 v[80:81], v[56:57], v[96:97], v[80:81]
	v_and_b32_e32 v93, 0xffff0000, v78
	v_pk_add_f32 v[80:81], v[8:9], v[80:81]
	v_lshlrev_b32_e32 v108, 16, v94
	v_mul_f32_e32 v37, 0xbfb8aa3b, v80
	v_exp_f32_e32 v124, v37
	v_mul_f32_e32 v37, 0xbfb8aa3b, v81
	v_exp_f32_e32 v125, v37
	v_pk_fma_f32 v[92:93], v[20:21], v[92:93], v[126:127]
	v_lshlrev_b32_e32 v126, 16, v87
	v_pk_fma_f32 v[92:93], v[72:73], v[108:109], v[92:93]
	v_pk_add_f32 v[124:125], v[124:125], 1.0 op_sel_hi:[1,0]
	v_pk_add_f32 v[92:93], v[28:29], v[92:93]
	v_and_b32_e32 v127, 0xffff0000, v87
	v_and_b32_e32 v87, 0xffff0000, v95
	v_rcp_f32_e32 v37, v125
	s_nop 0
	v_mul_f32_e32 v81, v81, v37
	v_and_b32_e32 v125, 0xffff0000, v91
	v_rcp_f32_e32 v37, v124
	s_nop 0
	v_mul_f32_e32 v80, v80, v37
	v_lshlrev_b32_e32 v124, 16, v91
	v_pk_mul_f32 v[80:81], v[80:81], v[92:93]
	v_lshlrev_b32_e32 v82, 16, v83
	v_and_b32_e32 v83, 0xffff0000, v83
	v_pk_mul_f32 v[92:93], v[54:55], v[124:125]
; __device__ __forceinline__ u32x4 pack8(const float* v) { u32x4 w; w.x = pk2(v[0], v[1]); w.y = pk2(v[2], v[3]); w.z = pk2(v[4], v[5]); w.w = pk2(v[6], v[7]); return w; }
; __device__ __forceinline__ void unpack8(u32x4 w, float* v) { v[0] = bflo(w.x); v[1] = bfhi(w.x); v[2] = bflo(w.y); v[3] = bfhi(w.y); v[4] = bflo(w.z); v[5] = bfhi(w.z); v[6] = bflo(w.w); v[7] = bfhi(w.w); }
; __device__ __forceinline__ float siluf_(float x) { return x / (1.f + __expf(-x)); }
; __global__ void __launch_bounds__(NTHR, 2) mk_fwd(Args args) {
;     ...
;                         float gm[8], gc[8], gn[8], vm[8], vc[8], vn[8], o[8];
;                         unpack8(gp_, gm); unpack8(gc_, gc); unpack8(gn_, gn); unpack8(vp_, vm); unpack8(vc_, vc); unpack8(vn_, vn);
; #pragma unroll
;                         for (int e = 0; e < 8; ++e) {
;                             const float a = wg0[e] * gm[e] + wg1[e] * gc[e] + wg2[e] * gn[e] + bg[e];
;                             const float v = wv0[e] * vm[e] + wv1[e] * vc[e] + wv2[e] * vn[e] + bv[e];
;                             o[e] = siluf_(a) * v;
;                         }
;                         *(u32x4*)(ACT + (size_t)(t0 + r) * FF + j0) = pack8(o);
;                         gp_ = gc_; vp_ = vc_; gc_ = gn_; vc_ = vn_;
	v_lshlrev_b32_e32 v90, 16, v99
	v_and_b32_e32 v91, 0xffff0000, v99
	v_pk_fma_f32 v[82:83], v[2:3], v[82:83], v[92:93]
	v_lshlrev_b32_e32 v78, 16, v79
	v_pk_fma_f32 v[82:83], v[58:59], v[90:91], v[82:83]
	v_and_b32_e32 v79, 0xffff0000, v79
	v_pk_add_f32 v[82:83], v[10:11], v[82:83]
	v_lshlrev_b32_e32 v86, 16, v95
	v_mul_f32_e32 v37, 0xbfb8aa3b, v82
	v_exp_f32_e32 v92, v37
	v_mul_f32_e32 v37, 0xbfb8aa3b, v83
	v_exp_f32_e32 v93, v37
	v_pk_mul_f32 v[94:95], v[70:71], v[126:127]
	v_cvt_pk_bf16_f32 v80, v80, v81
	v_pk_fma_f32 v[78:79], v[22:23], v[78:79], v[94:95]
	v_pk_add_f32 v[92:93], v[92:93], 1.0 op_sel_hi:[1,0]
	v_pk_fma_f32 v[78:79], v[74:75], v[86:87], v[78:79]
	v_pk_add_f32 v[78:79], v[30:31], v[78:79]
	v_rcp_f32_e32 v37, v93
	s_nop 0
	v_mul_f32_e32 v83, v83, v37
	s_mov_b32 s0, 0x13f20000
	v_rcp_f32_e32 v37, v92
	s_nop 0
	v_mul_f32_e32 v82, v82, v37
	v_lshl_add_u64 v[92:93], v[100:101], 0, v[42:43]
	v_pk_mul_f32 v[82:83], v[82:83], v[78:79]
	v_cvt_pk_bf16_f32 v79, v76, v77
	v_add_co_u32_e32 v76, vcc, s0, v92
	v_cvt_pk_bf16_f32 v78, v114, v115
	v_cvt_pk_bf16_f32 v81, v82, v83
	v_addc_co_u32_e32 v77, vcc, 0, v93, vcc
	s_mov_b32 s0, 0x89a5000
	global_store_dwordx4 v[76:77], v[78:81], off
	v_add_co_u32_e32 v76, vcc, s0, v104
	s_mov_b32 s0, 0x89a6000
	s_nop 0
	v_addc_co_u32_e32 v77, vcc, 0, v105, vcc
	s_nop 0
	v_add_co_u32_e32 v80, vcc, s0, v104
	v_pk_mul_f32 v[114:115], v[32:33], v[38:39]
	s_nop 0
	v_addc_co_u32_e32 v81, vcc, 0, v105, vcc
	s_nop 0
	v_pk_fma_f32 v[110:111], v[4:5], v[110:111], v[114:115]
	s_waitcnt vmcnt(6)
	v_mov_b32_e32 v76, v148
	v_mov_b32_e32 v77, v149
	v_mov_b32_e32 v78, v150
	v_mov_b32_e32 v79, v151
	v_lshlrev_b32_e32 v98, 16, v76
	v_and_b32_e32 v99, 0xffff0000, v76
	v_pk_fma_f32 v[110:111], v[48:49], v[98:99], v[110:111]
	s_waitcnt vmcnt(5)
	v_mov_b32_e32 v80, v152
	v_mov_b32_e32 v81, v153
	v_mov_b32_e32 v82, v154
	v_mov_b32_e32 v83, v155
	v_lshlrev_b32_e32 v94, 16, v80
	v_pk_add_f32 v[110:111], v[12:13], v[110:111]
	v_and_b32_e32 v95, 0xffff0000, v80
	v_mul_f32_e32 v37, 0xbfb8aa3b, v110
	v_exp_f32_e32 v114, v37
	v_mul_f32_e32 v37, 0xbfb8aa3b, v111
	v_exp_f32_e32 v115, v37
	v_pk_fma_f32 v[112:113], v[64:65], v[94:95], v[112:113]
	v_pk_add_f32 v[114:115], v[114:115], 1.0 op_sel_hi:[1,0]
	s_nop 0
	v_pk_add_f32 v[112:113], v[24:25], v[112:113]
	v_rcp_f32_e32 v37, v115
	s_nop 0
	v_mul_f32_e32 v111, v111, v37
	s_nop 0
	v_rcp_f32_e32 v37, v114
	s_nop 0
	v_mul_f32_e32 v110, v110, v37
	v_pk_mul_f32 v[128:129], v[110:111], v[112:113]
	v_lshlrev_b32_e32 v112, 16, v77
	v_and_b32_e32 v113, 0xffff0000, v77
	v_pk_mul_f32 v[76:77], v[34:35], v[88:89]
	v_lshlrev_b32_e32 v110, 16, v81
	v_pk_fma_f32 v[76:77], v[6:7], v[116:117], v[76:77]
	v_and_b32_e32 v111, 0xffff0000, v81
	v_pk_fma_f32 v[76:77], v[50:51], v[112:113], v[76:77]
	v_pk_mul_f32 v[114:115], v[62:63], v[84:85]
	v_pk_add_f32 v[76:77], v[14:15], v[76:77]
	v_pk_fma_f32 v[114:115], v[18:19], v[118:119], v[114:115]
	v_mul_f32_e32 v37, 0xbfb8aa3b, v76
	v_exp_f32_e32 v80, v37
	v_mul_f32_e32 v37, 0xbfb8aa3b, v77
	v_exp_f32_e32 v81, v37
	v_pk_fma_f32 v[114:115], v[66:67], v[110:111], v[114:115]
	v_pk_add_f32 v[80:81], v[80:81], 1.0 op_sel_hi:[1,0]
	s_nop 0
	v_pk_add_f32 v[114:115], v[26:27], v[114:115]
	v_rcp_f32_e32 v37, v81
	s_nop 0
	v_mul_f32_e32 v77, v77, v37
	s_nop 0
	v_rcp_f32_e32 v37, v80
	s_nop 0
	v_mul_f32_e32 v76, v76, v37
	v_pk_mul_f32 v[80:81], v[52:53], v[96:97]
	v_lshlrev_b32_e32 v116, 16, v78
	v_and_b32_e32 v117, 0xffff0000, v78
	v_pk_fma_f32 v[80:81], v[0:1], v[120:121], v[80:81]
	v_pk_mul_f32 v[76:77], v[76:77], v[114:115]
	v_pk_fma_f32 v[80:81], v[56:57], v[116:117], v[80:81]
	v_lshlrev_b32_e32 v114, 16, v82
	v_pk_add_f32 v[80:81], v[8:9], v[80:81]
	v_and_b32_e32 v115, 0xffff0000, v82
	v_mul_f32_e32 v37, 0xbfb8aa3b, v80
	v_exp_f32_e32 v118, v37
	v_mul_f32_e32 v37, 0xbfb8aa3b, v81
	v_exp_f32_e32 v119, v37
	v_pk_mul_f32 v[120:121], v[68:69], v[108:109]
	v_pk_add_f32 v[118:119], v[118:119], 1.0 op_sel_hi:[1,0]
	s_nop 0
	v_pk_fma_f32 v[120:121], v[20:21], v[122:123], v[120:121]
	v_rcp_f32_e32 v37, v119
	s_nop 0
	v_mul_f32_e32 v81, v81, v37
	v_pk_fma_f32 v[120:121], v[72:73], v[114:115], v[120:121]
	v_pk_add_f32 v[120:121], v[28:29], v[120:121]
	v_rcp_f32_e32 v37, v118
	s_nop 0
	v_mul_f32_e32 v80, v80, v37
	v_pk_mul_f32 v[80:81], v[80:81], v[120:121]
	v_lshlrev_b32_e32 v120, 16, v79
	v_and_b32_e32 v121, 0xffff0000, v79
	v_pk_mul_f32 v[78:79], v[54:55], v[90:91]
	v_lshlrev_b32_e32 v118, 16, v83
	v_pk_fma_f32 v[78:79], v[2:3], v[124:125], v[78:79]
	v_and_b32_e32 v119, 0xffff0000, v83
	v_pk_fma_f32 v[78:79], v[58:59], v[120:121], v[78:79]
	v_pk_mul_f32 v[122:123], v[70:71], v[86:87]
	v_pk_add_f32 v[78:79], v[10:11], v[78:79]
	v_pk_fma_f32 v[122:123], v[22:23], v[126:127], v[122:123]
	v_mul_f32_e32 v37, 0xbfb8aa3b, v78
	v_exp_f32_e32 v82, v37
	v_mul_f32_e32 v37, 0xbfb8aa3b, v79
	v_exp_f32_e32 v83, v37
	v_pk_fma_f32 v[122:123], v[74:75], v[118:119], v[122:123]
	v_cvt_pk_bf16_f32 v80, v80, v81
	v_pk_add_f32 v[122:123], v[30:31], v[122:123]
	v_pk_add_f32 v[82:83], v[82:83], 1.0 op_sel_hi:[1,0]
	s_nop 0
	s_nop 0
	v_rcp_f32_e32 v37, v83
	s_nop 0
	v_mul_f32_e32 v79, v79, v37
	s_mov_b32 s0, 0x13f21000
	v_rcp_f32_e32 v37, v82
	s_nop 0
	v_mul_f32_e32 v78, v78, v37
	v_pk_mul_f32 v[82:83], v[78:79], v[122:123]
	v_cvt_pk_bf16_f32 v79, v76, v77
	v_add_co_u32_e32 v76, vcc, s0, v92
	v_cvt_pk_bf16_f32 v78, v128, v129
	v_cvt_pk_bf16_f32 v81, v82, v83
	v_addc_co_u32_e32 v77, vcc, 0, v93, vcc
	s_mov_b32 s0, 0x89a8000
	global_store_dwordx4 v[76:77], v[78:81], off offset:1536
	v_add_co_u32_e32 v76, vcc, s0, v104
	s_mov_b32 s0, 0x89a9000
	s_nop 0
	v_addc_co_u32_e32 v77, vcc, 0, v105, vcc
	s_nop 0
	v_add_co_u32_e32 v76, vcc, s0, v104
	v_pk_mul_f32 v[126:127], v[32:33], v[98:99]
	s_nop 0
	v_addc_co_u32_e32 v77, vcc, 0, v105, vcc
	s_nop 0
	v_pk_fma_f32 v[38:39], v[4:5], v[38:39], v[126:127]
	v_pk_mul_f32 v[128:129], v[60:61], v[94:95]
	s_waitcnt vmcnt(5)
; __device__ __forceinline__ u32x4 pack8(const float* v) { u32x4 w; w.x = pk2(v[0], v[1]); w.y = pk2(v[2], v[3]); w.z = pk2(v[4], v[5]); w.w = pk2(v[6], v[7]); return w; }
; __device__ __forceinline__ void unpack8(u32x4 w, float* v) { v[0] = bflo(w.x); v[1] = bfhi(w.x); v[2] = bflo(w.y); v[3] = bfhi(w.y); v[4] = bflo(w.z); v[5] = bfhi(w.z); v[6] = bflo(w.w); v[7] = bfhi(w.w); }
; __device__ __forceinline__ float siluf_(float x) { return x / (1.f + __expf(-x)); }
; __global__ void __launch_bounds__(NTHR, 2) mk_fwd(Args args) {
;     ...
;                         u32x4 gn_ = (u32x4){0u, 0u, 0u, 0u}, vn_ = (u32x4){0u, 0u, 0u, 0u};
;                         const int ii = i0 + r;
;                         if (ii != LC - 1 && ii != TB - 1) { gn_ = *(const u32x4*)(up + (size_t)(r + 1) * FF2); vn_ = *(const u32x4*)(up + (size_t)(r + 1) * FF2 + FF); }
;                         float gm[8], gc[8], gn[8], vm[8], vc[8], vn[8], o[8];
;                         unpack8(gp_, gm); unpack8(gc_, gc); unpack8(gn_, gn); unpack8(vp_, vm); unpack8(vc_, vc); unpack8(vn_, vn);
; #pragma unroll
;                         for (int e = 0; e < 8; ++e) {
;                             const float a = wg0[e] * gm[e] + wg1[e] * gc[e] + wg2[e] * gn[e] + bg[e];
;                             const float v = wv0[e] * vm[e] + wv1[e] * vc[e] + wv2[e] * vn[e] + bv[e];
;                             o[e] = siluf_(a) * v;
;                         }
;                         *(u32x4*)(ACT + (size_t)(t0 + r) * FF + j0) = pack8(o);
;                         gp_ = gc_; vp_ = vc_; gc_ = gn_; vc_ = vn_;
	v_mov_b32_e32 v80, v156
	v_mov_b32_e32 v81, v157
	v_mov_b32_e32 v82, v158
	v_mov_b32_e32 v83, v159
	v_lshlrev_b32_e32 v124, 16, v80
	v_and_b32_e32 v125, 0xffff0000, v80
	v_pk_fma_f32 v[38:39], v[48:49], v[124:125], v[38:39]
	v_pk_fma_f32 v[106:107], v[16:17], v[106:107], v[128:129]
	v_pk_add_f32 v[38:39], v[12:13], v[38:39]
	s_waitcnt vmcnt(4)
	v_mov_b32_e32 v76, v160
	v_mov_b32_e32 v77, v161
	v_mov_b32_e32 v78, v162
	v_mov_b32_e32 v79, v163
	v_lshlrev_b32_e32 v122, 16, v76
	v_mul_f32_e32 v37, 0xbfb8aa3b, v38
	v_exp_f32_e32 v126, v37
	v_mul_f32_e32 v37, 0xbfb8aa3b, v39
	v_exp_f32_e32 v127, v37
	v_and_b32_e32 v123, 0xffff0000, v76
	v_pk_fma_f32 v[106:107], v[64:65], v[122:123], v[106:107]
	v_pk_add_f32 v[126:127], v[126:127], 1.0 op_sel_hi:[1,0]
	s_nop 0
	v_pk_add_f32 v[106:107], v[24:25], v[106:107]
	v_rcp_f32_e32 v37, v127
	s_nop 0
	v_mul_f32_e32 v39, v39, v37
	s_nop 0
	v_pk_mul_f32 v[128:129], v[34:35], v[112:113]
	v_rcp_f32_e32 v37, v126
	s_nop 0
	v_mul_f32_e32 v38, v38, v37
	v_lshlrev_b32_e32 v126, 16, v81
	v_and_b32_e32 v127, 0xffff0000, v81
	v_pk_fma_f32 v[88:89], v[6:7], v[88:89], v[128:129]
	v_pk_mul_f32 v[130:131], v[62:63], v[110:111]
	v_pk_fma_f32 v[88:89], v[50:51], v[126:127], v[88:89]
	v_pk_fma_f32 v[84:85], v[18:19], v[84:85], v[130:131]
	v_pk_add_f32 v[88:89], v[14:15], v[88:89]
	v_pk_mul_f32 v[38:39], v[38:39], v[106:107]
	v_mul_f32_e32 v37, 0xbfb8aa3b, v88
	v_exp_f32_e32 v128, v37
	v_mul_f32_e32 v37, 0xbfb8aa3b, v89
	v_exp_f32_e32 v129, v37
	v_lshlrev_b32_e32 v106, 16, v77
	v_and_b32_e32 v107, 0xffff0000, v77
	v_pk_fma_f32 v[84:85], v[66:67], v[106:107], v[84:85]
	v_pk_add_f32 v[128:129], v[128:129], 1.0 op_sel_hi:[1,0]
	v_pk_add_f32 v[84:85], v[26:27], v[84:85]
	s_nop 0
	v_rcp_f32_e32 v37, v129
	s_nop 0
	v_mul_f32_e32 v89, v89, v37
	v_pk_mul_f32 v[134:135], v[68:69], v[114:115]
	v_rcp_f32_e32 v37, v128
	s_nop 0
	v_mul_f32_e32 v88, v88, v37
	v_pk_mul_f32 v[84:85], v[88:89], v[84:85]
	v_pk_mul_f32 v[88:89], v[52:53], v[116:117]
	v_lshlrev_b32_e32 v130, 16, v82
	v_and_b32_e32 v131, 0xffff0000, v82
	v_pk_fma_f32 v[88:89], v[0:1], v[96:97], v[88:89]
	v_pk_fma_f32 v[108:109], v[20:21], v[108:109], v[134:135]
	v_pk_fma_f32 v[88:89], v[56:57], v[130:131], v[88:89]
	v_lshlrev_b32_e32 v128, 16, v78
	v_pk_add_f32 v[88:89], v[8:9], v[88:89]
	v_and_b32_e32 v129, 0xffff0000, v78
	v_mul_f32_e32 v37, 0xbfb8aa3b, v88
	v_exp_f32_e32 v96, v37
	v_mul_f32_e32 v37, 0xbfb8aa3b, v89
	v_exp_f32_e32 v97, v37
	v_pk_fma_f32 v[108:109], v[72:73], v[128:129], v[108:109]
	v_pk_add_f32 v[96:97], v[96:97], 1.0 op_sel_hi:[1,0]
	s_nop 0
	v_pk_add_f32 v[108:109], v[28:29], v[108:109]
	v_rcp_f32_e32 v37, v97
	s_nop 0
	v_mul_f32_e32 v89, v89, v37
	v_pk_mul_f32 v[136:137], v[70:71], v[118:119]
	v_rcp_f32_e32 v37, v96
	s_nop 0
	v_mul_f32_e32 v88, v88, v37
	v_pk_mul_f32 v[134:135], v[54:55], v[120:121]
	v_pk_mul_f32 v[88:89], v[88:89], v[108:109]
	v_lshlrev_b32_e32 v108, 16, v83
	v_and_b32_e32 v109, 0xffff0000, v83
	v_pk_fma_f32 v[90:91], v[2:3], v[90:91], v[134:135]
	v_pk_fma_f32 v[86:87], v[22:23], v[86:87], v[136:137]
	v_pk_fma_f32 v[90:91], v[58:59], v[108:109], v[90:91]
	v_lshlrev_b32_e32 v96, 16, v79
	v_pk_add_f32 v[90:91], v[10:11], v[90:91]
	v_and_b32_e32 v97, 0xffff0000, v79
	v_mul_f32_e32 v37, 0xbfb8aa3b, v90
	v_exp_f32_e32 v134, v37
	v_mul_f32_e32 v37, 0xbfb8aa3b, v91
	v_exp_f32_e32 v135, v37
	v_pk_fma_f32 v[86:87], v[74:75], v[96:97], v[86:87]
	v_cvt_pk_bf16_f32 v88, v88, v89
	v_pk_add_f32 v[86:87], v[30:31], v[86:87]
	v_pk_add_f32 v[134:135], v[134:135], 1.0 op_sel_hi:[1,0]
	s_nop 0
	s_nop 0
	v_rcp_f32_e32 v37, v135
	s_nop 0
	v_mul_f32_e32 v91, v91, v37
	s_nop 0
	v_rcp_f32_e32 v37, v134
	s_nop 0
	v_mul_f32_e32 v90, v90, v37
	v_pk_mul_f32 v[90:91], v[90:91], v[86:87]
	v_cvt_pk_bf16_f32 v86, v38, v39
	v_add_co_u32_e32 v38, vcc, 0x13f22000, v92
	v_cvt_pk_bf16_f32 v87, v84, v85
	v_cvt_pk_bf16_f32 v89, v90, v91
	v_addc_co_u32_e32 v39, vcc, 0, v93, vcc
	global_store_dwordx4 v[38:39], v[86:89], off offset:3072
	v_mov_b32_e32 v38, v36
	v_mov_b32_e32 v39, v36
	v_mov_b32_e32 v37, v36
	v_mov_b64_e32 v[90:91], v[38:39]
	v_mov_b64_e32 v[86:87], v[38:39]
	v_cmp_ne_u32_e32 vcc, s18, v132
	v_mov_b64_e32 v[88:89], v[36:37]
	v_mov_b64_e32 v[84:85], v[36:37]
	s_and_saveexec_b64 s[0:1], vcc
	s_cbranch_execz .LBB0_90
	v_add_co_u32_e32 v38, vcc, 0x89ab000, v104
	s_nop 1
	v_addc_co_u32_e32 v39, vcc, 0, v105, vcc
	v_add_co_u32_e32 v84, vcc, 0x89ac000, v104
	s_nop 1
	v_addc_co_u32_e32 v85, vcc, 0, v105, vcc
	s_waitcnt vmcnt(4)
	v_mov_b32_e32 v88, v164
	v_mov_b32_e32 v89, v165
	v_mov_b32_e32 v90, v166
	v_mov_b32_e32 v91, v167
	s_nop 0
	s_waitcnt vmcnt(3)
	v_mov_b32_e32 v84, v168
	v_mov_b32_e32 v85, v169
	v_mov_b32_e32 v86, v170
	v_mov_b32_e32 v87, v171
	s_branch .LBB0_90
